# attention schedule variant: MERGEW=0
# speedup vs baseline: 1.0045x; 1.0045x over previous
; #define MFMA(a, b, c) __builtin_amdgcn_mfma_f32_32x32x16_bf16((a), (b), (c), 0, 0, 0)
; #define SBAR() __builtin_amdgcn_sched_barrier(0)
; __device__ __forceinline__ void at_finishSM(f32x16& p0, f32x16& p1, float alpha, float& l_reg, bf16x8& pa0, bf16x8& pa1, bf16x8& pa2, bf16x8& pa3) {
;     ...
;   PK4(p0, 0, pa0); PK4(p0, 8, pa1); PK4(p1, 0, pa2); PK4(p1, 8, pa3);
;     ...
; }
; __device__ __forceinline__ void at_qkt(f32x16& p0, f32x16& p1, const char* Ks, const bf16x8* qr, int r32, int hi, float negm) {
; #pragma unroll
;   for (int r = 0; r < 16; ++r) { p0[r] = negm; p1[r] = negm; }
; #pragma unroll
;   for (int d0 = 0; d0 < 6; ++d0) {
;     const bf16x8 b0 = *(const bf16x8*)(Ks + r32 * AT_KROW + d0 * 32 + hi * 16);
;     const bf16x8 b1 = *(const bf16x8*)(Ks + (32 + r32) * AT_KROW + d0 * 32 + hi * 16);
;     p0 = MFMA(b0, qr[d0], p0);
;     p1 = MFMA(b1, qr[d0], p1);
;   }
; }
; __device__ __forceinline__ int v_st(int k, int c) { const int kk = (k & ~0xC) | ((k & 4) << 1) | ((k & 8) >> 1); return ((kk >> 3) * 4 + (c >> 5)) * 512 + ((kk & 7) * 32 + (c & 31)) * 2; }
; __device__ __forceinline__ int v_rd_base(int lane) { return ((lane & 3) << 3) | (((lane >> 2) & 3) << 6) | (((lane >> 4) & 1) << 5) | (((lane >> 5) & 1) << 8); }
; template <int OFF> __device__ __forceinline__ s16x4 tr_read(int vb) {
;   s16x4 r; asm volatile("ds_read_b64_tr_b16 %0, %1 offset:%2" : "=&v"(r) : "v"(vb), "i"(OFF) : "memory"); return r;
; }
; template <int D0> __device__ __forceinline__ void pv_one(f32x16& od, int vb, bf16x8 pa0, bf16x8 pa1, bf16x8 pa2, bf16x8 pa3) {
;   const s16x4 l0 = tr_read<v_rd_off(D0, 0, 0)>(vb), h0 = tr_read<v_rd_off(D0, 0, 1)>(vb), l1 = tr_read<v_rd_off(D0, 1, 0)>(vb), h1 = tr_read<v_rd_off(D0, 1, 1)>(vb);
;   const s16x4 l2 = tr_read<v_rd_off(D0, 2, 0)>(vb), h2 = tr_read<v_rd_off(D0, 2, 1)>(vb), l3 = tr_read<v_rd_off(D0, 3, 0)>(vb), h3 = tr_read<v_rd_off(D0, 3, 1)>(vb);
;   asm volatile("s_waitcnt lgkmcnt(0)" ::: "memory"); SBAR();
;     ...
;   od = MFMA(pa0, PK(l0, h0), od);
;   od = MFMA(pa1, PK(l1, h1), od);
;   od = MFMA(pa2, PK(l2, h2), od);
;   od = MFMA(pa3, PK(l3, h3), od);
;     ...
; }
; __device__ __forceinline__ void pv_d0(f32x16* o, int vb, bf16x8 pa0, bf16x8 pa1, bf16x8 pa2, bf16x8 pa3) {
;   pv_one<0>(o[0], vb, pa0, pa1, pa2, pa3); pv_one<1>(o[1], vb, pa0, pa1, pa2, pa3);
.Lat_rare_t130_back:
	v_add_f32_e32 v173, v173, v175
	v_cvt_pk_bf16_f32 v104, v32, v33
	v_cvt_pk_bf16_f32 v105, v34, v35
	v_cvt_pk_bf16_f32 v106, v36, v37
	v_cvt_pk_bf16_f32 v107, v38, v39
	v_cvt_pk_bf16_f32 v108, v40, v41
	v_cvt_pk_bf16_f32 v109, v42, v43
	v_cvt_pk_bf16_f32 v110, v44, v45
	v_cvt_pk_bf16_f32 v111, v46, v47
	v_cvt_pk_bf16_f32 v112, v48, v49
	v_cvt_pk_bf16_f32 v113, v50, v51
	v_cvt_pk_bf16_f32 v114, v52, v53
	v_cvt_pk_bf16_f32 v115, v54, v55
	v_cvt_pk_bf16_f32 v116, v56, v57
	v_cvt_pk_bf16_f32 v117, v58, v59
	v_cvt_pk_bf16_f32 v118, v60, v61
	v_cvt_pk_bf16_f32 v119, v62, v63
	ds_read_b128 v[184:187], v170 offset:39936
	ds_read_b128 v[188:191], v170 offset:46592
	ds_read_b128 v[192:195], v170 offset:39968
	ds_read_b128 v[196:199], v170 offset:46624
	s_barrier
	ds_read_b128 v[200:203], v170 offset:40000
	ds_read_b128 v[204:207], v170 offset:46656
	s_waitcnt lgkmcnt(5)
	v_mfma_f32_32x32x16_bf16 v[32:47], v[184:187], v[80:83], v[64:79]
	s_waitcnt lgkmcnt(4)
	v_mfma_f32_32x32x16_bf16 v[48:63], v[188:191], v[80:83], v[64:79]
	ds_read_b128 v[208:211], v170 offset:40032
	ds_read_b128 v[212:215], v170 offset:46688
	s_waitcnt lgkmcnt(5)
	v_mfma_f32_32x32x16_bf16 v[32:47], v[192:195], v[84:87], v[32:47]
	s_waitcnt lgkmcnt(4)
	v_mfma_f32_32x32x16_bf16 v[48:63], v[196:199], v[84:87], v[48:63]
	ds_read_b128 v[184:187], v170 offset:40064
	ds_read_b128 v[188:191], v170 offset:46720
	s_waitcnt lgkmcnt(5)
	v_mfma_f32_32x32x16_bf16 v[32:47], v[200:203], v[88:91], v[32:47]
	s_waitcnt lgkmcnt(4)
	v_mfma_f32_32x32x16_bf16 v[48:63], v[204:207], v[88:91], v[48:63]
	ds_read_b128 v[192:195], v170 offset:40096
	ds_read_b128 v[196:199], v170 offset:46752
	s_waitcnt lgkmcnt(5)
	v_mfma_f32_32x32x16_bf16 v[32:47], v[208:211], v[92:95], v[32:47]
	s_waitcnt lgkmcnt(4)
	v_mfma_f32_32x32x16_bf16 v[48:63], v[212:215], v[92:95], v[48:63]
	ds_read_b64_tr_b16 v[148:149], v171 offset:32768
	ds_read_b64_tr_b16 v[150:151], v171 offset:34816
	ds_read_b64_tr_b16 v[152:153], v171 offset:36864
	ds_read_b64_tr_b16 v[154:155], v171 offset:38912
	s_waitcnt lgkmcnt(7)
	v_mfma_f32_32x32x16_bf16 v[32:47], v[184:187], v[96:99], v[32:47]
	s_waitcnt lgkmcnt(6)
	v_mfma_f32_32x32x16_bf16 v[48:63], v[188:191], v[96:99], v[48:63]
	ds_read_b64_tr_b16 v[156:157], v171 offset:40960
	ds_read_b64_tr_b16 v[158:159], v171 offset:43008
	ds_read_b64_tr_b16 v[216:217], v171 offset:45056
	ds_read_b64_tr_b16 v[218:219], v171 offset:47104
	s_waitcnt lgkmcnt(9)
	v_mfma_f32_32x32x16_bf16 v[32:47], v[192:195], v[100:103], v[32:47]
	s_waitcnt lgkmcnt(8)
	v_mfma_f32_32x32x16_bf16 v[48:63], v[196:199], v[100:103], v[48:63]
	ds_read_b64_tr_b16 v[220:221], v171 offset:33280
	ds_read_b64_tr_b16 v[222:223], v171 offset:35328
	ds_read_b64_tr_b16 v[224:225], v171 offset:37376
	ds_read_b64_tr_b16 v[226:227], v171 offset:39424
	s_waitcnt lgkmcnt(10)
	v_mfma_f32_32x32x16_bf16 v[0:15], v[104:107], v[148:151], v[0:15]
	s_waitcnt lgkmcnt(8)
	v_mfma_f32_32x32x16_bf16 v[0:15], v[108:111], v[152:155], v[0:15]
	ds_read_b64_tr_b16 v[236:237], v171 offset:41472
	ds_read_b64_tr_b16 v[238:239], v171 offset:43520
	ds_read_b64_tr_b16 v[240:241], v171 offset:45568
	ds_read_b64_tr_b16 v[242:243], v171 offset:47616
	s_waitcnt lgkmcnt(10)
	v_mfma_f32_32x32x16_bf16 v[0:15], v[112:115], v[156:159], v[0:15]
	s_waitcnt lgkmcnt(8)
	v_mfma_f32_32x32x16_bf16 v[0:15], v[116:119], v[216:219], v[0:15]
	s_waitcnt lgkmcnt(6)
	v_mfma_f32_32x32x16_bf16 v[16:31], v[104:107], v[220:223], v[16:31]
	s_waitcnt lgkmcnt(4)
	v_mfma_f32_32x32x16_bf16 v[16:31], v[108:111], v[224:227], v[16:31]
	s_waitcnt lgkmcnt(2)
	v_mfma_f32_32x32x16_bf16 v[16:31], v[112:115], v[236:239], v[16:31]
	s_waitcnt lgkmcnt(0)
	v_mfma_f32_32x32x16_bf16 v[16:31], v[116:119], v[240:243], v[16:31]
	s_barrier
; __device__ __forceinline__ int crow(int r, int hi) { return (r & 3) + 8 * (r >> 2) + 4 * hi; }
; __device__ __forceinline__ void at_finishSM(f32x16& p0, f32x16& p1, float alpha, float& l_reg, bf16x8& pa0, bf16x8& pa1, bf16x8& pa2, bf16x8& pa3) {
; #pragma unroll
;   for (int r = 0; r < 16; ++r) p1[r] = __builtin_amdgcn_exp2f(p1[r]);
;   float ps = 0;
; #pragma unroll
;   for (int r = 0; r < 16; ++r) ps += p0[r];
; #pragma unroll
;   for (int r = 0; r < 16; ++r) ps += p1[r];
;   { auto rr = __builtin_amdgcn_permlane32_swap(__float_as_uint(ps), __float_as_uint(ps), false, false);
;     ps = __uint_as_float(rr[0]) + __uint_as_float(rr[1]); }
;   l_reg = l_reg * alpha + ps;
; __device__ void phase_attn(const Params& p, char* lds) {
;     ...
;     bf16_t* Gw = G1 + (row0 + qblk * 256 + wid * 32) * 1024 + h * 64 + r32;
;     bf16_t gin[32];
; #pragma unroll
;     for (int r = 0; r < 16; ++r) { gin[2 * r] = Gw[(size_t)crow(r, hi) * 1024]; gin[2 * r + 1] = Gw[(size_t)crow(r, hi) * 1024 + 32]; }
	s_add_u32 s8, s28, 0x0
	s_addc_u32 s9, s29, 0
	global_load_ushort v120, v235, s[8:9] offset:0
	global_load_ushort v121, v235, s[8:9] offset:64
	global_load_ushort v122, v235, s[8:9] offset:2048
	global_load_ushort v123, v235, s[8:9] offset:2112
	s_add_u32 s8, s28, 0x1000
	s_addc_u32 s9, s29, 0
	global_load_ushort v124, v235, s[8:9] offset:0
	global_load_ushort v125, v235, s[8:9] offset:64
	global_load_ushort v126, v235, s[8:9] offset:2048
	global_load_ushort v127, v235, s[8:9] offset:2112
	s_add_u32 s8, s28, 0x4000
	s_addc_u32 s9, s29, 0
	global_load_ushort v132, v235, s[8:9] offset:0
	global_load_ushort v133, v235, s[8:9] offset:64
	global_load_ushort v134, v235, s[8:9] offset:2048
	global_load_ushort v135, v235, s[8:9] offset:2112
	s_add_u32 s8, s28, 0x5000
	s_addc_u32 s9, s29, 0
	global_load_ushort v136, v235, s[8:9] offset:0
	global_load_ushort v137, v235, s[8:9] offset:64
	global_load_ushort v138, v235, s[8:9] offset:2048
	global_load_ushort v139, v235, s[8:9] offset:2112
	s_add_u32 s8, s28, 0x8000
	s_addc_u32 s9, s29, 0
	global_load_ushort v140, v235, s[8:9] offset:0
	global_load_ushort v141, v235, s[8:9] offset:64
	global_load_ushort v142, v235, s[8:9] offset:2048
	global_load_ushort v143, v235, s[8:9] offset:2112
	s_add_u32 s8, s28, 0x9000
	s_addc_u32 s9, s29, 0
	global_load_ushort v144, v235, s[8:9] offset:0
	global_load_ushort v145, v235, s[8:9] offset:64
	global_load_ushort v146, v235, s[8:9] offset:2048
	global_load_ushort v147, v235, s[8:9] offset:2112
	s_add_u32 s8, s28, 0xc000
	s_addc_u32 s9, s29, 0
	global_load_ushort v200, v235, s[8:9] offset:0
	global_load_ushort v201, v235, s[8:9] offset:64
	global_load_ushort v202, v235, s[8:9] offset:2048
	global_load_ushort v203, v235, s[8:9] offset:2112
	s_add_u32 s8, s28, 0xd000
	s_addc_u32 s9, s29, 0
	global_load_ushort v204, v235, s[8:9] offset:0
	global_load_ushort v205, v235, s[8:9] offset:64
	global_load_ushort v206, v235, s[8:9] offset:2048
	global_load_ushort v207, v235, s[8:9] offset:2112
	v_exp_f32_e32 v32, v32
	v_exp_f32_e32 v48, v48
	v_exp_f32_e32 v33, v33
	v_exp_f32_e32 v49, v49
	v_exp_f32_e32 v34, v34
	v_exp_f32_e32 v50, v50
	v_exp_f32_e32 v35, v35
	v_exp_f32_e32 v51, v51
	v_exp_f32_e32 v36, v36
	v_exp_f32_e32 v52, v52
	v_exp_f32_e32 v37, v37
	v_exp_f32_e32 v53, v53
	v_exp_f32_e32 v38, v38
	v_exp_f32_e32 v54, v54
	v_exp_f32_e32 v39, v39
	v_exp_f32_e32 v55, v55
	v_exp_f32_e32 v40, v40
	v_exp_f32_e32 v56, v56
	v_exp_f32_e32 v41, v41
	v_exp_f32_e32 v57, v57
	v_exp_f32_e32 v42, v42
	v_exp_f32_e32 v58, v58
	v_exp_f32_e32 v43, v43
	v_exp_f32_e32 v59, v59
	v_exp_f32_e32 v44, v44
	v_exp_f32_e32 v60, v60
	v_exp_f32_e32 v45, v45
	v_exp_f32_e32 v61, v61
	v_exp_f32_e32 v46, v46
	v_exp_f32_e32 v62, v62
	v_exp_f32_e32 v47, v47
	v_exp_f32_e32 v63, v63
	v_add_f32_e32 v175, v32, v33
	v_add_f32_e32 v174, v48, v49
	v_add_f32_e32 v175, v175, v34
	v_add_f32_e32 v174, v174, v50
	v_add_f32_e32 v175, v175, v35
	v_add_f32_e32 v174, v174, v51
	v_add_f32_e32 v175, v175, v36
	v_add_f32_e32 v174, v174, v52
	v_add_f32_e32 v175, v175, v37
	v_add_f32_e32 v174, v174, v53
	v_add_f32_e32 v175, v175, v38
	v_add_f32_e32 v174, v174, v54
	v_add_f32_e32 v175, v175, v39
	v_add_f32_e32 v174, v174, v55
	v_add_f32_e32 v175, v175, v40
	v_add_f32_e32 v174, v174, v56
	v_add_f32_e32 v175, v175, v41
	v_add_f32_e32 v174, v174, v57
	v_add_f32_e32 v175, v175, v42
	v_add_f32_e32 v174, v174, v58
	v_add_f32_e32 v175, v175, v43
	v_add_f32_e32 v174, v174, v59
	v_add_f32_e32 v175, v175, v44
	v_add_f32_e32 v174, v174, v60
	v_add_f32_e32 v175, v175, v45
	v_add_f32_e32 v174, v174, v61
	v_add_f32_e32 v175, v175, v46
	v_add_f32_e32 v174, v174, v62
	v_add_f32_e32 v175, v175, v47
	v_add_f32_e32 v174, v174, v63
	v_add_f32_e32 v175, v175, v174
	v_cmp_ge_f32_e32 vcc, s23, v175
	s_cmp_eq_u64 vcc, exec
	s_cbranch_scc0 .Lat_rare_t131
